# stacked latency hoists on the reversed-order version: rope stores widened and issued after the next loads, batched final-epilogue slot polls, GLA pass-0 early operand prefetch
# speedup vs baseline: 1.0134x; 1.0040x over previous
.LBB0_354:
	v_mov_b32_e32 v37, v36
	v_mov_b32_e32 v8, v36
	v_mov_b32_e32 v9, v36
	v_pk_mul_f32 v[2:3], v[2:3], v[8:9]
	v_pk_mul_f32 v[0:1], v[0:1], v[36:37]
	v_pk_mul_f32 v[6:7], v[6:7], v[8:9]
	v_pk_mul_f32 v[4:5], v[4:5], v[36:37]
	s_waitcnt vmcnt(0)
	v_pk_mul_f32 v[8:9], v[0:1], v[20:21]
	v_pk_mul_f32 v[10:11], v[2:3], v[22:23]
	v_pk_mul_f32 v[0:1], v[0:1], v[16:17]
	v_pk_mul_f32 v[2:3], v[2:3], v[18:19]
	v_pk_fma_f32 v[10:11], v[6:7], v[18:19], v[10:11] neg_lo:[0,0,1] neg_hi:[0,0,1]
	v_pk_fma_f32 v[8:9], v[4:5], v[16:17], v[8:9] neg_lo:[0,0,1] neg_hi:[0,0,1]
	v_pk_fma_f32 v[2:3], v[6:7], v[22:23], v[2:3]
	v_pk_fma_f32 v[0:1], v[4:5], v[20:21], v[0:1]
	v_cvt_pk_bf16_f32 v210, v8, v9
	v_cvt_pk_bf16_f32 v211, v10, v11
	v_cvt_pk_bf16_f32 v214, v0, v1
	v_cvt_pk_bf16_f32 v215, v2, v3
	global_store_dwordx4 v[30:31], v[208:211], off
	global_store_dwordx4 v[30:31], v[212:215], off offset:64

.LBB0_376:
	s_lshl_b32 s19, s36, 8
	s_or_b32 s38, s19, s57
	s_ashr_i32 s39, s38, 31
	s_lshl_b64 s[38:39], s[38:39], 1
	s_add_u32 s19, s58, s38
	s_addc_u32 s21, s59, s39
	s_and_b64 s[38:39], s[8:9], exec
	s_waitcnt lgkmcnt(0)
	v_mul_f32_e32 v130, 0x3e38aa3b, v129
	s_cselect_b32 s39, s21, s60
	s_cselect_b32 s38, s19, s61
	v_lshlrev_b32_e32 v150, 1, v152
	v_cndmask_b32_e64 v176, v129, v130, s[8:9]
	v_ashrrev_i32_e32 v167, 31, v166
	s_cselect_b32 s19, 9, 7
	v_lshl_add_u64 v[168:169], s[38:39], 0, v[150:151]
	v_lshlrev_b64 v[130:131], s19, v[166:167]
	v_pk_mul_f32 v[122:123], v[122:123], v[176:177] op_sel_hi:[1,0]
	v_pk_mul_f32 v[120:121], v[120:121], v[176:177] op_sel_hi:[1,0]
	v_lshl_add_u64 v[174:175], v[130:131], 1, v[168:169]
	v_pk_mul_f32 v[126:127], v[126:127], v[176:177] op_sel_hi:[1,0]
	v_pk_mul_f32 v[124:125], v[124:125], v[176:177] op_sel_hi:[1,0]
	s_waitcnt vmcnt(0)
	v_pk_mul_f32 v[130:131], v[120:121], v[134:135]
	v_pk_mul_f32 v[194:195], v[122:123], v[136:137]
	v_pk_mul_f32 v[120:121], v[120:121], v[138:139]
	v_pk_mul_f32 v[122:123], v[122:123], v[140:141]
	v_pk_fma_f32 v[194:195], v[126:127], v[140:141], v[194:195] neg_lo:[0,0,1] neg_hi:[0,0,1]
	v_pk_fma_f32 v[130:131], v[124:125], v[138:139], v[130:131] neg_lo:[0,0,1] neg_hi:[0,0,1]
	v_pk_fma_f32 v[122:123], v[126:127], v[136:137], v[122:123]
	v_pk_fma_f32 v[120:121], v[124:125], v[134:135], v[120:121]
	v_cvt_pk_bf16_f32 v200, v130, v131
	v_cvt_pk_bf16_f32 v201, v194, v195
	v_cvt_pk_bf16_f32 v204, v120, v121
	v_cvt_pk_bf16_f32 v205, v122, v123
	s_and_b64 vcc, exec, s[6:7]
	v_mov_b32_e32 v133, 0
	v_mov_b32_e32 v134, 0
	v_mov_b32_e32 v135, 0
	v_mov_b32_e32 v129, 1.0
	v_mov_b32_e32 v130, 1.0
	v_mov_b32_e32 v131, 1.0
	s_cbranch_vccnz .LBB0_378
	global_load_dwordx4 v[128:131], v[170:171], off offset:16
	global_load_dwordx4 v[132:135], v[172:173], off offset:16
.LBB0_378:
	v_mov_b32_e32 v177, v176
	v_mov_b32_e32 v120, v176
	v_mov_b32_e32 v121, v176
	v_pk_mul_f32 v[114:115], v[114:115], v[120:121]
	v_pk_mul_f32 v[112:113], v[112:113], v[176:177]
	v_pk_mul_f32 v[118:119], v[118:119], v[120:121]
	v_pk_mul_f32 v[116:117], v[116:117], v[176:177]
	s_waitcnt vmcnt(0)
	v_pk_mul_f32 v[120:121], v[112:113], v[132:133]
	v_pk_mul_f32 v[122:123], v[114:115], v[134:135]
	v_pk_mul_f32 v[112:113], v[112:113], v[128:129]
	v_pk_mul_f32 v[114:115], v[114:115], v[130:131]
	v_pk_fma_f32 v[112:113], v[116:117], v[132:133], v[112:113]
	v_pk_fma_f32 v[114:115], v[118:119], v[134:135], v[114:115]
	v_cvt_pk_bf16_f32 v206, v112, v113
	v_cvt_pk_bf16_f32 v207, v114, v115
	v_or_b32_e32 v114, 16, v166
	ds_read_b32 v113, v192 offset:64
	v_cmp_gt_i32_e32 vcc, s54, v114
	v_pk_fma_f32 v[122:123], v[118:119], v[130:131], v[122:123] neg_lo:[0,0,1] neg_hi:[0,0,1]
	v_pk_fma_f32 v[120:121], v[116:117], v[128:129], v[120:121] neg_lo:[0,0,1] neg_hi:[0,0,1]
	v_cndmask_b32_e32 v112, v186, v187, vcc
	v_bitop3_b32 v112, v112, v166, 16 bitop3:0xe0
	v_cvt_pk_bf16_f32 v202, v120, v121
	v_cvt_pk_bf16_f32 v203, v122, v123
	v_lshlrev_b32_e32 v150, 7, v112
	v_lshl_add_u64 v[128:129], v[154:155], 0, v[150:151]
	v_lshl_add_u64 v[130:131], v[156:157], 0, v[150:151]
	v_mov_b32_e32 v112, 1.0
	v_mov_b32_e32 v116, 0
	s_and_b64 vcc, exec, s[6:7]
	v_mov_b32_e32 v118, 0
	v_mov_b32_e32 v119, 0
	v_mov_b32_e32 v120, 0
	v_mov_b32_e32 v121, 0
	v_mov_b32_e32 v122, 1.0
	v_mov_b32_e32 v123, 1.0
	v_mov_b32_e32 v124, 1.0
	v_mov_b32_e32 v125, 1.0
	s_cbranch_vccnz .LBB0_380
	global_load_dwordx4 v[122:125], v[128:129], off
	global_load_dwordx4 v[118:121], v[130:131], off
.LBB0_380:
	global_store_dwordx4 v[174:175], v[204:207], off offset:64
	global_store_dwordx4 v[174:175], v[200:203], off
	s_waitcnt lgkmcnt(0)
	v_mul_f32_e32 v115, 0x3e38aa3b, v113
	v_cndmask_b32_e64 v132, v113, v115, s[8:9]
	v_ashrrev_i32_e32 v115, 31, v114
	v_lshlrev_b64 v[114:115], s19, v[114:115]
	v_pk_mul_f32 v[106:107], v[106:107], v[132:133] op_sel_hi:[1,0]
	v_pk_mul_f32 v[104:105], v[104:105], v[132:133] op_sel_hi:[1,0]
	v_lshl_add_u64 v[126:127], v[114:115], 1, v[168:169]
	v_pk_mul_f32 v[110:111], v[110:111], v[132:133] op_sel_hi:[1,0]
	v_pk_mul_f32 v[108:109], v[108:109], v[132:133] op_sel_hi:[1,0]
	s_waitcnt vmcnt(2)
	v_pk_mul_f32 v[114:115], v[104:105], v[118:119]
	v_pk_mul_f32 v[134:135], v[106:107], v[120:121]
	v_pk_mul_f32 v[104:105], v[104:105], v[122:123]
	v_pk_mul_f32 v[106:107], v[106:107], v[124:125]
	v_pk_fma_f32 v[134:135], v[110:111], v[124:125], v[134:135] neg_lo:[0,0,1] neg_hi:[0,0,1]
	v_pk_fma_f32 v[114:115], v[108:109], v[122:123], v[114:115] neg_lo:[0,0,1] neg_hi:[0,0,1]
	v_pk_fma_f32 v[106:107], v[110:111], v[120:121], v[106:107]
	v_pk_fma_f32 v[104:105], v[108:109], v[118:119], v[104:105]
	v_cvt_pk_bf16_f32 v208, v114, v115
	v_cvt_pk_bf16_f32 v209, v134, v135
	v_cvt_pk_bf16_f32 v212, v104, v105
	v_cvt_pk_bf16_f32 v213, v106, v107
	s_and_b64 vcc, exec, s[6:7]
	v_mov_b32_e32 v117, 0
	v_mov_b32_e32 v118, 0
	v_mov_b32_e32 v119, 0
	v_mov_b32_e32 v113, 1.0
	v_mov_b32_e32 v114, 1.0
	v_mov_b32_e32 v115, 1.0
	s_cbranch_vccnz .LBB0_382
	global_load_dwordx4 v[112:115], v[128:129], off offset:16
	global_load_dwordx4 v[116:119], v[130:131], off offset:16
.LBB0_382:
	v_mov_b32_e32 v133, v132
	v_mov_b32_e32 v104, v132
	v_mov_b32_e32 v105, v132
	v_pk_mul_f32 v[98:99], v[98:99], v[104:105]
	v_pk_mul_f32 v[96:97], v[96:97], v[132:133]
	v_pk_mul_f32 v[102:103], v[102:103], v[104:105]
	v_pk_mul_f32 v[100:101], v[100:101], v[132:133]
	s_waitcnt vmcnt(0)
	v_pk_mul_f32 v[104:105], v[96:97], v[116:117]
	v_pk_mul_f32 v[106:107], v[98:99], v[118:119]
	v_pk_mul_f32 v[96:97], v[96:97], v[112:113]
	v_pk_mul_f32 v[98:99], v[98:99], v[114:115]
	v_pk_fma_f32 v[96:97], v[100:101], v[116:117], v[96:97]
	v_pk_fma_f32 v[98:99], v[102:103], v[118:119], v[98:99]
	v_cvt_pk_bf16_f32 v214, v96, v97
	v_cvt_pk_bf16_f32 v215, v98, v99
	v_or_b32_e32 v98, 32, v166
	ds_read_b32 v97, v192 offset:128
	v_cmp_gt_i32_e32 vcc, s54, v98
	v_pk_fma_f32 v[106:107], v[102:103], v[114:115], v[106:107] neg_lo:[0,0,1] neg_hi:[0,0,1]
	v_pk_fma_f32 v[104:105], v[100:101], v[112:113], v[104:105] neg_lo:[0,0,1] neg_hi:[0,0,1]
	v_cndmask_b32_e32 v96, v188, v189, vcc
	v_bitop3_b32 v96, v96, v166, 32 bitop3:0xe0
	v_cvt_pk_bf16_f32 v210, v104, v105
	v_cvt_pk_bf16_f32 v211, v106, v107
	v_lshlrev_b32_e32 v150, 7, v96
	v_lshl_add_u64 v[112:113], v[154:155], 0, v[150:151]
	v_lshl_add_u64 v[114:115], v[156:157], 0, v[150:151]
	v_mov_b32_e32 v96, 1.0
	v_mov_b32_e32 v100, 0
	s_and_b64 vcc, exec, s[6:7]
	v_mov_b32_e32 v102, 0
	v_mov_b32_e32 v103, 0
	v_mov_b32_e32 v104, 0
	v_mov_b32_e32 v105, 0
	v_mov_b32_e32 v106, 1.0
	v_mov_b32_e32 v107, 1.0
	v_mov_b32_e32 v108, 1.0
	v_mov_b32_e32 v109, 1.0
	s_cbranch_vccnz .LBB0_384
	global_load_dwordx4 v[106:109], v[112:113], off
	global_load_dwordx4 v[102:105], v[114:115], off
.LBB0_384:
	global_store_dwordx4 v[126:127], v[212:215], off offset:64
	global_store_dwordx4 v[126:127], v[208:211], off
	s_waitcnt lgkmcnt(0)
	v_mul_f32_e32 v99, 0x3e38aa3b, v97
	v_cndmask_b32_e64 v116, v97, v99, s[8:9]
	v_ashrrev_i32_e32 v99, 31, v98
	v_lshlrev_b64 v[98:99], s19, v[98:99]
	v_pk_mul_f32 v[90:91], v[90:91], v[116:117] op_sel_hi:[1,0]
	v_pk_mul_f32 v[88:89], v[88:89], v[116:117] op_sel_hi:[1,0]
	v_lshl_add_u64 v[110:111], v[98:99], 1, v[168:169]
	v_pk_mul_f32 v[94:95], v[94:95], v[116:117] op_sel_hi:[1,0]
	v_pk_mul_f32 v[92:93], v[92:93], v[116:117] op_sel_hi:[1,0]
	s_waitcnt vmcnt(2)
	v_pk_mul_f32 v[98:99], v[88:89], v[102:103]
	v_pk_mul_f32 v[118:119], v[90:91], v[104:105]
	v_pk_mul_f32 v[88:89], v[88:89], v[106:107]
	v_pk_mul_f32 v[90:91], v[90:91], v[108:109]
	v_pk_fma_f32 v[118:119], v[94:95], v[108:109], v[118:119] neg_lo:[0,0,1] neg_hi:[0,0,1]
	v_pk_fma_f32 v[98:99], v[92:93], v[106:107], v[98:99] neg_lo:[0,0,1] neg_hi:[0,0,1]
	v_pk_fma_f32 v[90:91], v[94:95], v[104:105], v[90:91]
	v_pk_fma_f32 v[88:89], v[92:93], v[102:103], v[88:89]
	v_cvt_pk_bf16_f32 v200, v98, v99
	v_cvt_pk_bf16_f32 v201, v118, v119
	v_cvt_pk_bf16_f32 v204, v88, v89
	v_cvt_pk_bf16_f32 v205, v90, v91
	s_and_b64 vcc, exec, s[6:7]
	v_mov_b32_e32 v101, 0
	v_mov_b32_e32 v102, 0
	v_mov_b32_e32 v103, 0
	v_mov_b32_e32 v97, 1.0
	v_mov_b32_e32 v98, 1.0
	v_mov_b32_e32 v99, 1.0
	s_cbranch_vccnz .LBB0_386
	global_load_dwordx4 v[96:99], v[112:113], off offset:16
	global_load_dwordx4 v[100:103], v[114:115], off offset:16
.LBB0_386:
	v_mov_b32_e32 v117, v116
	v_mov_b32_e32 v88, v116
	v_mov_b32_e32 v89, v116
	v_pk_mul_f32 v[82:83], v[82:83], v[88:89]
	v_pk_mul_f32 v[80:81], v[80:81], v[116:117]
	v_pk_mul_f32 v[86:87], v[86:87], v[88:89]
	v_pk_mul_f32 v[84:85], v[84:85], v[116:117]
	s_waitcnt vmcnt(0)
	v_pk_mul_f32 v[88:89], v[80:81], v[100:101]
	v_pk_mul_f32 v[90:91], v[82:83], v[102:103]
	v_pk_mul_f32 v[80:81], v[80:81], v[96:97]
	v_pk_mul_f32 v[82:83], v[82:83], v[98:99]
	v_pk_fma_f32 v[80:81], v[84:85], v[100:101], v[80:81]
	v_pk_fma_f32 v[82:83], v[86:87], v[102:103], v[82:83]
	v_cvt_pk_bf16_f32 v206, v80, v81
	v_cvt_pk_bf16_f32 v207, v82, v83
	v_or_b32_e32 v82, 48, v166
	ds_read_b32 v81, v192 offset:192
	v_cmp_gt_i32_e32 vcc, s54, v82
	v_pk_fma_f32 v[90:91], v[86:87], v[98:99], v[90:91] neg_lo:[0,0,1] neg_hi:[0,0,1]
	v_pk_fma_f32 v[88:89], v[84:85], v[96:97], v[88:89] neg_lo:[0,0,1] neg_hi:[0,0,1]
	v_cndmask_b32_e32 v80, v190, v191, vcc
	v_bitop3_b32 v80, v80, v166, 48 bitop3:0xe0
	v_cvt_pk_bf16_f32 v202, v88, v89
	v_cvt_pk_bf16_f32 v203, v90, v91
	v_lshlrev_b32_e32 v150, 7, v80
	v_lshl_add_u64 v[96:97], v[154:155], 0, v[150:151]
	v_lshl_add_u64 v[98:99], v[156:157], 0, v[150:151]
	v_mov_b32_e32 v80, 1.0
	v_mov_b32_e32 v84, 0
	s_and_b64 vcc, exec, s[6:7]
	v_mov_b32_e32 v86, 0
	v_mov_b32_e32 v87, 0
	v_mov_b32_e32 v88, 0
	v_mov_b32_e32 v89, 0
	v_mov_b32_e32 v90, 1.0
	v_mov_b32_e32 v91, 1.0
	v_mov_b32_e32 v92, 1.0
	v_mov_b32_e32 v93, 1.0
	s_cbranch_vccnz .LBB0_388
	global_load_dwordx4 v[90:93], v[96:97], off
	global_load_dwordx4 v[86:89], v[98:99], off
.LBB0_388:
	global_store_dwordx4 v[110:111], v[204:207], off offset:64
	global_store_dwordx4 v[110:111], v[200:203], off
	s_waitcnt lgkmcnt(0)
	v_mul_f32_e32 v83, 0x3e38aa3b, v81
	v_cndmask_b32_e64 v100, v81, v83, s[8:9]
	v_ashrrev_i32_e32 v83, 31, v82
	v_lshlrev_b64 v[82:83], s19, v[82:83]
	v_pk_mul_f32 v[74:75], v[74:75], v[100:101] op_sel_hi:[1,0]
	v_pk_mul_f32 v[72:73], v[72:73], v[100:101] op_sel_hi:[1,0]
	v_lshl_add_u64 v[94:95], v[82:83], 1, v[168:169]
	v_pk_mul_f32 v[78:79], v[78:79], v[100:101] op_sel_hi:[1,0]
	v_pk_mul_f32 v[76:77], v[76:77], v[100:101] op_sel_hi:[1,0]
	s_waitcnt vmcnt(2)
	v_pk_mul_f32 v[82:83], v[72:73], v[86:87]
	v_pk_mul_f32 v[102:103], v[74:75], v[88:89]
	v_pk_mul_f32 v[72:73], v[72:73], v[90:91]
	v_pk_mul_f32 v[74:75], v[74:75], v[92:93]
	v_pk_fma_f32 v[102:103], v[78:79], v[92:93], v[102:103] neg_lo:[0,0,1] neg_hi:[0,0,1]
	v_pk_fma_f32 v[82:83], v[76:77], v[90:91], v[82:83] neg_lo:[0,0,1] neg_hi:[0,0,1]
	v_pk_fma_f32 v[74:75], v[78:79], v[88:89], v[74:75]
	v_pk_fma_f32 v[72:73], v[76:77], v[86:87], v[72:73]
	v_cvt_pk_bf16_f32 v208, v82, v83
	v_cvt_pk_bf16_f32 v209, v102, v103
	v_cvt_pk_bf16_f32 v212, v72, v73
	v_cvt_pk_bf16_f32 v213, v74, v75
	s_and_b64 vcc, exec, s[6:7]
	v_mov_b32_e32 v85, 0
	v_mov_b32_e32 v86, 0
	v_mov_b32_e32 v87, 0
	v_mov_b32_e32 v81, 1.0
	v_mov_b32_e32 v82, 1.0
	v_mov_b32_e32 v83, 1.0
	s_cbranch_vccnz .LBB0_390
	global_load_dwordx4 v[80:83], v[96:97], off offset:16
	global_load_dwordx4 v[84:87], v[98:99], off offset:16
.LBB0_390:
	v_mov_b32_e32 v101, v100
	v_mov_b32_e32 v72, v100
	v_mov_b32_e32 v73, v100
	v_pk_mul_f32 v[66:67], v[66:67], v[72:73]
	v_pk_mul_f32 v[64:65], v[64:65], v[100:101]
	v_pk_mul_f32 v[70:71], v[70:71], v[72:73]
	v_pk_mul_f32 v[68:69], v[68:69], v[100:101]
	s_waitcnt vmcnt(0)
	v_pk_mul_f32 v[72:73], v[64:65], v[84:85]
	v_pk_mul_f32 v[74:75], v[66:67], v[86:87]
	v_pk_mul_f32 v[64:65], v[64:65], v[80:81]
	v_pk_mul_f32 v[66:67], v[66:67], v[82:83]
	v_pk_fma_f32 v[64:65], v[68:69], v[84:85], v[64:65]
	v_pk_fma_f32 v[66:67], v[70:71], v[86:87], v[66:67]
	v_cvt_pk_bf16_f32 v214, v64, v65
	v_cvt_pk_bf16_f32 v215, v66, v67
	ds_read_b32 v65, v192 offset:512
	v_cmp_gt_i32_e32 vcc, s66, v166
	v_add_u32_e32 v66, 0x80, v166
	v_pk_fma_f32 v[74:75], v[70:71], v[82:83], v[74:75] neg_lo:[0,0,1] neg_hi:[0,0,1]
	v_cndmask_b32_e32 v64, v184, v185, vcc
	v_pk_fma_f32 v[72:73], v[68:69], v[80:81], v[72:73] neg_lo:[0,0,1] neg_hi:[0,0,1]
	v_and_b32_e32 v64, v64, v66
	v_cvt_pk_bf16_f32 v210, v72, v73
	v_cvt_pk_bf16_f32 v211, v74, v75
	v_lshlrev_b32_e32 v150, 7, v64
	v_lshl_add_u64 v[80:81], v[154:155], 0, v[150:151]
	v_lshl_add_u64 v[82:83], v[156:157], 0, v[150:151]
	v_mov_b32_e32 v64, 1.0
	v_mov_b32_e32 v68, 0
	s_and_b64 vcc, exec, s[6:7]
	v_mov_b32_e32 v70, 0
	v_mov_b32_e32 v71, 0
	v_mov_b32_e32 v72, 0
	v_mov_b32_e32 v73, 0
	v_mov_b32_e32 v74, 1.0
	v_mov_b32_e32 v75, 1.0
	v_mov_b32_e32 v76, 1.0
	v_mov_b32_e32 v77, 1.0
	s_cbranch_vccnz .LBB0_392
	global_load_dwordx4 v[74:77], v[80:81], off
	global_load_dwordx4 v[70:73], v[82:83], off
.LBB0_392:
	global_store_dwordx4 v[94:95], v[212:215], off offset:64
	global_store_dwordx4 v[94:95], v[208:211], off
	s_waitcnt lgkmcnt(0)
	v_mul_f32_e32 v67, 0x3e38aa3b, v65
	v_cndmask_b32_e64 v84, v65, v67, s[8:9]
	v_ashrrev_i32_e32 v67, 31, v66
	v_lshlrev_b64 v[66:67], s19, v[66:67]
	v_pk_mul_f32 v[58:59], v[58:59], v[84:85] op_sel_hi:[1,0]
	v_pk_mul_f32 v[56:57], v[56:57], v[84:85] op_sel_hi:[1,0]
	v_lshl_add_u64 v[78:79], v[66:67], 1, v[168:169]
	v_pk_mul_f32 v[62:63], v[62:63], v[84:85] op_sel_hi:[1,0]
	v_pk_mul_f32 v[60:61], v[60:61], v[84:85] op_sel_hi:[1,0]
	s_waitcnt vmcnt(2)
	v_pk_mul_f32 v[66:67], v[56:57], v[70:71]
	v_pk_mul_f32 v[86:87], v[58:59], v[72:73]
	v_pk_mul_f32 v[56:57], v[56:57], v[74:75]
	v_pk_mul_f32 v[58:59], v[58:59], v[76:77]
	v_pk_fma_f32 v[86:87], v[62:63], v[76:77], v[86:87] neg_lo:[0,0,1] neg_hi:[0,0,1]
	v_pk_fma_f32 v[66:67], v[60:61], v[74:75], v[66:67] neg_lo:[0,0,1] neg_hi:[0,0,1]
	v_pk_fma_f32 v[58:59], v[62:63], v[72:73], v[58:59]
	v_pk_fma_f32 v[56:57], v[60:61], v[70:71], v[56:57]
	v_cvt_pk_bf16_f32 v200, v66, v67
	v_cvt_pk_bf16_f32 v201, v86, v87
	v_cvt_pk_bf16_f32 v204, v56, v57
	v_cvt_pk_bf16_f32 v205, v58, v59
	s_and_b64 vcc, exec, s[6:7]
	v_mov_b32_e32 v69, 0
	v_mov_b32_e32 v70, 0
	v_mov_b32_e32 v71, 0
	v_mov_b32_e32 v65, 1.0
	v_mov_b32_e32 v66, 1.0
	v_mov_b32_e32 v67, 1.0
	s_cbranch_vccnz .LBB0_394
	global_load_dwordx4 v[64:67], v[80:81], off offset:16
	global_load_dwordx4 v[68:71], v[82:83], off offset:16
.LBB0_394:
	v_mov_b32_e32 v85, v84
	v_mov_b32_e32 v56, v84
	v_mov_b32_e32 v57, v84
	v_pk_mul_f32 v[50:51], v[50:51], v[56:57]
	v_pk_mul_f32 v[48:49], v[48:49], v[84:85]
	v_pk_mul_f32 v[54:55], v[54:55], v[56:57]
	v_pk_mul_f32 v[52:53], v[52:53], v[84:85]
	s_waitcnt vmcnt(0)
	v_pk_mul_f32 v[56:57], v[48:49], v[68:69]
	v_pk_mul_f32 v[58:59], v[50:51], v[70:71]
	v_pk_mul_f32 v[48:49], v[48:49], v[64:65]
	v_pk_mul_f32 v[50:51], v[50:51], v[66:67]
	v_pk_fma_f32 v[48:49], v[52:53], v[68:69], v[48:49]
	v_pk_fma_f32 v[50:51], v[54:55], v[70:71], v[50:51]
	v_cvt_pk_bf16_f32 v206, v48, v49
	v_cvt_pk_bf16_f32 v207, v50, v51
	ds_read_b32 v49, v192 offset:576
	v_cmp_gt_i32_e32 vcc, s67, v166
	v_add_u32_e32 v50, 0x90, v166
	v_pk_fma_f32 v[58:59], v[54:55], v[66:67], v[58:59] neg_lo:[0,0,1] neg_hi:[0,0,1]
	v_cndmask_b32_e32 v48, v186, v187, vcc
	v_pk_fma_f32 v[56:57], v[52:53], v[64:65], v[56:57] neg_lo:[0,0,1] neg_hi:[0,0,1]
	v_and_b32_e32 v48, v48, v50
	v_cvt_pk_bf16_f32 v202, v56, v57
	v_cvt_pk_bf16_f32 v203, v58, v59
	v_lshlrev_b32_e32 v150, 7, v48
	v_lshl_add_u64 v[64:65], v[154:155], 0, v[150:151]
	v_lshl_add_u64 v[66:67], v[156:157], 0, v[150:151]
	v_mov_b32_e32 v48, 1.0
	v_mov_b32_e32 v52, 0
	s_and_b64 vcc, exec, s[6:7]
	v_mov_b32_e32 v54, 0
	v_mov_b32_e32 v55, 0
	v_mov_b32_e32 v56, 0
	v_mov_b32_e32 v57, 0
	v_mov_b32_e32 v58, 1.0
	v_mov_b32_e32 v59, 1.0
	v_mov_b32_e32 v60, 1.0
	v_mov_b32_e32 v61, 1.0
	s_cbranch_vccnz .LBB0_396
	global_load_dwordx4 v[58:61], v[64:65], off
	global_load_dwordx4 v[54:57], v[66:67], off
.LBB0_396:
	global_store_dwordx4 v[78:79], v[204:207], off offset:64
	global_store_dwordx4 v[78:79], v[200:203], off
	s_waitcnt lgkmcnt(0)
	v_mul_f32_e32 v51, 0x3e38aa3b, v49
	v_cndmask_b32_e64 v68, v49, v51, s[8:9]
	v_ashrrev_i32_e32 v51, 31, v50
	v_lshlrev_b64 v[50:51], s19, v[50:51]
	v_pk_mul_f32 v[42:43], v[42:43], v[68:69] op_sel_hi:[1,0]
	v_pk_mul_f32 v[40:41], v[40:41], v[68:69] op_sel_hi:[1,0]
	v_lshl_add_u64 v[62:63], v[50:51], 1, v[168:169]
	v_pk_mul_f32 v[46:47], v[46:47], v[68:69] op_sel_hi:[1,0]
	v_pk_mul_f32 v[44:45], v[44:45], v[68:69] op_sel_hi:[1,0]
	s_waitcnt vmcnt(2)
	v_pk_mul_f32 v[50:51], v[40:41], v[54:55]
	v_pk_mul_f32 v[70:71], v[42:43], v[56:57]
	v_pk_mul_f32 v[40:41], v[40:41], v[58:59]
	v_pk_mul_f32 v[42:43], v[42:43], v[60:61]
	v_pk_fma_f32 v[70:71], v[46:47], v[60:61], v[70:71] neg_lo:[0,0,1] neg_hi:[0,0,1]
	v_pk_fma_f32 v[50:51], v[44:45], v[58:59], v[50:51] neg_lo:[0,0,1] neg_hi:[0,0,1]
	v_pk_fma_f32 v[42:43], v[46:47], v[56:57], v[42:43]
	v_pk_fma_f32 v[40:41], v[44:45], v[54:55], v[40:41]
	v_cvt_pk_bf16_f32 v208, v50, v51
	v_cvt_pk_bf16_f32 v209, v70, v71
	v_cvt_pk_bf16_f32 v212, v40, v41
	v_cvt_pk_bf16_f32 v213, v42, v43
	s_and_b64 vcc, exec, s[6:7]
	v_mov_b32_e32 v53, 0
	v_mov_b32_e32 v54, 0
	v_mov_b32_e32 v55, 0
	v_mov_b32_e32 v49, 1.0
	v_mov_b32_e32 v50, 1.0
	v_mov_b32_e32 v51, 1.0
	s_cbranch_vccnz .LBB0_398
	global_load_dwordx4 v[48:51], v[64:65], off offset:16
	global_load_dwordx4 v[52:55], v[66:67], off offset:16
.LBB0_398:
	v_mov_b32_e32 v69, v68
	v_mov_b32_e32 v40, v68
	v_mov_b32_e32 v41, v68
	v_pk_mul_f32 v[34:35], v[34:35], v[40:41]
	v_pk_mul_f32 v[32:33], v[32:33], v[68:69]
	v_pk_mul_f32 v[38:39], v[38:39], v[40:41]
	v_pk_mul_f32 v[36:37], v[36:37], v[68:69]
	s_waitcnt vmcnt(0)
	v_pk_mul_f32 v[40:41], v[32:33], v[52:53]
	v_pk_mul_f32 v[42:43], v[34:35], v[54:55]
	v_pk_mul_f32 v[32:33], v[32:33], v[48:49]
	v_pk_mul_f32 v[34:35], v[34:35], v[50:51]
	v_pk_fma_f32 v[32:33], v[36:37], v[52:53], v[32:33]
	v_pk_fma_f32 v[34:35], v[38:39], v[54:55], v[34:35]
	v_cvt_pk_bf16_f32 v214, v32, v33
	v_cvt_pk_bf16_f32 v215, v34, v35
	ds_read_b32 v33, v192 offset:640
	v_cmp_gt_i32_e32 vcc, s68, v166
	v_add_u32_e32 v34, 0xa0, v166
	v_pk_fma_f32 v[42:43], v[38:39], v[50:51], v[42:43] neg_lo:[0,0,1] neg_hi:[0,0,1]
	v_cndmask_b32_e32 v32, v188, v189, vcc
	v_pk_fma_f32 v[40:41], v[36:37], v[48:49], v[40:41] neg_lo:[0,0,1] neg_hi:[0,0,1]
	v_and_b32_e32 v32, v32, v34
	v_cvt_pk_bf16_f32 v210, v40, v41
	v_cvt_pk_bf16_f32 v211, v42, v43
	v_lshlrev_b32_e32 v150, 7, v32
	v_lshl_add_u64 v[48:49], v[154:155], 0, v[150:151]
	v_lshl_add_u64 v[50:51], v[156:157], 0, v[150:151]
	v_mov_b32_e32 v32, 1.0
	v_mov_b32_e32 v36, 0
	s_and_b64 vcc, exec, s[6:7]
	v_mov_b32_e32 v38, 0
	v_mov_b32_e32 v39, 0
	v_mov_b32_e32 v40, 0
	v_mov_b32_e32 v41, 0
	v_mov_b32_e32 v42, 1.0
	v_mov_b32_e32 v43, 1.0
	v_mov_b32_e32 v44, 1.0
	v_mov_b32_e32 v45, 1.0
	s_cbranch_vccnz .LBB0_400
	global_load_dwordx4 v[42:45], v[48:49], off
	global_load_dwordx4 v[38:41], v[50:51], off
.LBB0_400:
	global_store_dwordx4 v[62:63], v[212:215], off offset:64
	global_store_dwordx4 v[62:63], v[208:211], off
	s_waitcnt lgkmcnt(0)
	v_mul_f32_e32 v35, 0x3e38aa3b, v33
	v_cndmask_b32_e64 v52, v33, v35, s[8:9]
	v_ashrrev_i32_e32 v35, 31, v34
	v_lshlrev_b64 v[34:35], s19, v[34:35]
	v_pk_mul_f32 v[26:27], v[26:27], v[52:53] op_sel_hi:[1,0]
	v_pk_mul_f32 v[24:25], v[24:25], v[52:53] op_sel_hi:[1,0]
	v_lshl_add_u64 v[46:47], v[34:35], 1, v[168:169]
	v_pk_mul_f32 v[30:31], v[30:31], v[52:53] op_sel_hi:[1,0]
	v_pk_mul_f32 v[28:29], v[28:29], v[52:53] op_sel_hi:[1,0]
	s_waitcnt vmcnt(2)
	v_pk_mul_f32 v[34:35], v[24:25], v[38:39]
	v_pk_mul_f32 v[54:55], v[26:27], v[40:41]
	v_pk_mul_f32 v[24:25], v[24:25], v[42:43]
	v_pk_mul_f32 v[26:27], v[26:27], v[44:45]
	v_pk_fma_f32 v[54:55], v[30:31], v[44:45], v[54:55] neg_lo:[0,0,1] neg_hi:[0,0,1]
	v_pk_fma_f32 v[34:35], v[28:29], v[42:43], v[34:35] neg_lo:[0,0,1] neg_hi:[0,0,1]
	v_pk_fma_f32 v[26:27], v[30:31], v[40:41], v[26:27]
	v_pk_fma_f32 v[24:25], v[28:29], v[38:39], v[24:25]
	v_cvt_pk_bf16_f32 v200, v34, v35
	v_cvt_pk_bf16_f32 v201, v54, v55
	v_cvt_pk_bf16_f32 v204, v24, v25
	v_cvt_pk_bf16_f32 v205, v26, v27
	s_and_b64 vcc, exec, s[6:7]
	v_mov_b32_e32 v37, 0
	v_mov_b32_e32 v38, 0
	v_mov_b32_e32 v39, 0
	v_mov_b32_e32 v33, 1.0
	v_mov_b32_e32 v34, 1.0
	v_mov_b32_e32 v35, 1.0
	s_cbranch_vccnz .LBB0_402
	global_load_dwordx4 v[32:35], v[48:49], off offset:16
	global_load_dwordx4 v[36:39], v[50:51], off offset:16
.LBB0_402:
	v_mov_b32_e32 v53, v52
	v_mov_b32_e32 v24, v52
	v_mov_b32_e32 v25, v52
	v_pk_mul_f32 v[18:19], v[18:19], v[24:25]
	v_pk_mul_f32 v[16:17], v[16:17], v[52:53]
	v_pk_mul_f32 v[22:23], v[22:23], v[24:25]
	v_pk_mul_f32 v[20:21], v[20:21], v[52:53]
	s_waitcnt vmcnt(0)
	v_pk_mul_f32 v[24:25], v[16:17], v[36:37]
	v_pk_mul_f32 v[26:27], v[18:19], v[38:39]
	v_pk_mul_f32 v[16:17], v[16:17], v[32:33]
	v_pk_mul_f32 v[18:19], v[18:19], v[34:35]
	v_pk_fma_f32 v[16:17], v[20:21], v[36:37], v[16:17]
	v_pk_fma_f32 v[18:19], v[22:23], v[38:39], v[18:19]
	v_cvt_pk_bf16_f32 v206, v16, v17
	v_cvt_pk_bf16_f32 v207, v18, v19
	ds_read_b32 v17, v192 offset:704
	v_cmp_gt_i32_e32 vcc, s69, v166
	v_add_u32_e32 v18, 0xb0, v166
	v_pk_fma_f32 v[26:27], v[22:23], v[34:35], v[26:27] neg_lo:[0,0,1] neg_hi:[0,0,1]
	v_cndmask_b32_e32 v16, v190, v191, vcc
	v_pk_fma_f32 v[24:25], v[20:21], v[32:33], v[24:25] neg_lo:[0,0,1] neg_hi:[0,0,1]
	v_and_b32_e32 v16, v16, v18
	v_cvt_pk_bf16_f32 v202, v24, v25
	v_cvt_pk_bf16_f32 v203, v26, v27
	v_lshlrev_b32_e32 v150, 7, v16
	v_lshl_add_u64 v[32:33], v[154:155], 0, v[150:151]
	v_lshl_add_u64 v[34:35], v[156:157], 0, v[150:151]
	v_mov_b32_e32 v16, 1.0
	v_mov_b32_e32 v20, 0
	s_and_b64 vcc, exec, s[6:7]
	v_mov_b32_e32 v22, 0
	v_mov_b32_e32 v23, 0
	v_mov_b32_e32 v24, 0
	v_mov_b32_e32 v25, 0
	v_mov_b32_e32 v26, 1.0
	v_mov_b32_e32 v27, 1.0
	v_mov_b32_e32 v28, 1.0
	v_mov_b32_e32 v29, 1.0
	s_cbranch_vccnz .LBB0_404
	global_load_dwordx4 v[26:29], v[32:33], off
	global_load_dwordx4 v[22:25], v[34:35], off
.LBB0_404:
	global_store_dwordx4 v[46:47], v[204:207], off offset:64
	global_store_dwordx4 v[46:47], v[200:203], off
	s_waitcnt lgkmcnt(0)
	v_mul_f32_e32 v19, 0x3e38aa3b, v17
	v_cndmask_b32_e64 v36, v17, v19, s[8:9]
	v_ashrrev_i32_e32 v19, 31, v18
	v_lshlrev_b64 v[18:19], s19, v[18:19]
	v_pk_mul_f32 v[10:11], v[10:11], v[36:37] op_sel_hi:[1,0]
	v_pk_mul_f32 v[8:9], v[8:9], v[36:37] op_sel_hi:[1,0]
	v_lshl_add_u64 v[30:31], v[18:19], 1, v[168:169]
	v_pk_mul_f32 v[14:15], v[14:15], v[36:37] op_sel_hi:[1,0]
	v_pk_mul_f32 v[12:13], v[12:13], v[36:37] op_sel_hi:[1,0]
	s_waitcnt vmcnt(2)
	v_pk_mul_f32 v[18:19], v[8:9], v[22:23]
	v_pk_mul_f32 v[38:39], v[10:11], v[24:25]
	v_pk_mul_f32 v[8:9], v[8:9], v[26:27]
	v_pk_mul_f32 v[10:11], v[10:11], v[28:29]
	v_pk_fma_f32 v[38:39], v[14:15], v[28:29], v[38:39] neg_lo:[0,0,1] neg_hi:[0,0,1]
	v_pk_fma_f32 v[18:19], v[12:13], v[26:27], v[18:19] neg_lo:[0,0,1] neg_hi:[0,0,1]
	v_pk_fma_f32 v[10:11], v[14:15], v[24:25], v[10:11]
	v_pk_fma_f32 v[8:9], v[12:13], v[22:23], v[8:9]
	v_cvt_pk_bf16_f32 v208, v18, v19
	v_cvt_pk_bf16_f32 v209, v38, v39
	v_cvt_pk_bf16_f32 v212, v8, v9
	v_cvt_pk_bf16_f32 v213, v10, v11
	s_and_b64 vcc, exec, s[6:7]
	v_mov_b32_e32 v21, 0
	v_mov_b32_e32 v22, 0
	v_mov_b32_e32 v23, 0
	v_mov_b32_e32 v17, 1.0
	v_mov_b32_e32 v18, 1.0
	v_mov_b32_e32 v19, 1.0
	s_cbranch_vccnz .LBB0_354
	global_load_dwordx4 v[16:19], v[32:33], off offset:16
	global_load_dwordx4 v[20:23], v[34:35], off offset:16
	s_branch .LBB0_354
